# nt hint on P0's once-read f32 x loads
# speedup vs baseline: 1.0129x; 1.0074x over previous
; __device__ __forceinline__ void p0_prologue(const Args& a, LAS unsigned char* lds, int gw, int NGW, int wave, int lane) {
;     ...
;     for (int m0 = gw; m0 < M; m0 += 8 * NGW) {
;         f32x4 v[8][4];
; #pragma unroll
;         for (int r = 0; r < 8; ++r) { const int m = m0 + r * NGW; const f32x4* xr = (const f32x4*)(a.x + (size_t)(m < M ? m : gw) * DM) + lane;
; #pragma unroll
;             for (int j = 0; j < 4; ++j) v[r][j] = xr[64 * j]; }
; #pragma unroll
;         for (int r = 0; r < 8; ++r) { const int m = m0 + r * NGW; if (m >= M) break;
;             float s = 0.f;
; #pragma unroll
;             for (int j = 0; j < 4; ++j) s += (v[r][j].x * v[r][j].x + v[r][j].y * v[r][j].y) + (v[r][j].z * v[r][j].z + v[r][j].w * v[r][j].w);
;             s = wave_sum(s);
;             if (lane == 0) ss0[m] = s;
.LBB0_440:
	s_add_i32 s5, s46, s47
	s_cmp_lt_i32 s5, 0x8000
	s_cselect_b64 s[36:37], -1, 0
	s_and_b64 s[16:17], s[36:37], exec
	s_cselect_b32 s16, s5, s4
	s_ashr_i32 s17, s16, 31
	s_add_i32 s5, s0, s5
	s_lshl_b64 s[16:17], s[16:17], 12
	global_load_dwordx4 v[124:127], v[138:139], off offset:-3072 nt
	global_load_dwordx4 v[120:123], v[138:139], off offset:-2048 nt
	global_load_dwordx4 v[116:119], v[138:139], off offset:-1024 nt
	global_load_dwordx4 v[112:115], v[138:139], off nt
	s_cmp_lt_i32 s5, 0x8000
	s_cselect_b64 s[34:35], -1, 0
	s_waitcnt vmcnt(8)
	v_lshl_add_u64 v[0:1], v[132:133], 0, s[16:17]
	s_and_b64 s[16:17], s[34:35], exec
	s_cselect_b32 s16, s5, s4
	s_ashr_i32 s17, s16, 31
	s_add_i32 s5, s0, s5
	s_lshl_b64 s[16:17], s[16:17], 12
	s_cmp_lt_i32 s5, 0x8000
	s_cselect_b64 s[30:31], -1, 0
	global_load_dwordx4 v[108:111], v[0:1], off nt
	global_load_dwordx4 v[104:107], v[0:1], off offset:1024 nt
	global_load_dwordx4 v[100:103], v[0:1], off offset:2048 nt
	global_load_dwordx4 v[96:99], v[0:1], off offset:3072 nt
	v_lshl_add_u64 v[0:1], v[132:133], 0, s[16:17]
	s_and_b64 s[16:17], s[30:31], exec
	s_cselect_b32 s16, s5, s4
	s_ashr_i32 s17, s16, 31
	s_add_i32 s5, s0, s5
	s_lshl_b64 s[16:17], s[16:17], 12
	s_cmp_lt_i32 s5, 0x8000
	s_cselect_b64 s[22:23], -1, 0
	global_load_dwordx4 v[92:95], v[0:1], off nt
	global_load_dwordx4 v[88:91], v[0:1], off offset:1024 nt
	global_load_dwordx4 v[80:83], v[0:1], off offset:2048 nt
	global_load_dwordx4 v[72:75], v[0:1], off offset:3072 nt
	v_lshl_add_u64 v[0:1], v[132:133], 0, s[16:17]
	s_and_b64 s[16:17], s[22:23], exec
	s_cselect_b32 s16, s5, s4
	s_ashr_i32 s17, s16, 31
	s_add_i32 s5, s0, s5
	s_lshl_b64 s[38:39], s[16:17], 12
	s_cmp_lt_i32 s5, 0x8000
	s_cselect_b64 s[20:21], -1, 0
	s_and_b64 s[16:17], s[20:21], exec
	s_cselect_b32 s16, s5, s4
	s_ashr_i32 s17, s16, 31
	s_add_i32 s5, s0, s5
	s_lshl_b64 s[50:51], s[16:17], 12
	s_cmp_lt_i32 s5, 0x8000
	s_cselect_b64 s[18:19], -1, 0
	s_and_b64 s[16:17], s[18:19], exec
	s_cselect_b32 s16, s5, s4
	s_ashr_i32 s17, s16, 31
	s_add_i32 s5, s0, s5
	s_lshl_b64 s[52:53], s[16:17], 12
	s_cmp_lt_i32 s5, 0x8000
	s_cselect_b64 s[16:17], -1, 0
	s_and_b64 s[64:65], s[16:17], exec
	s_cselect_b32 s64, s5, s4
	global_load_dwordx4 v[84:87], v[0:1], off nt
	global_load_dwordx4 v[76:79], v[0:1], off offset:1024 nt
	global_load_dwordx4 v[68:71], v[0:1], off offset:2048 nt
	global_load_dwordx4 v[64:67], v[0:1], off offset:3072 nt
	v_lshl_add_u64 v[0:1], v[132:133], 0, s[38:39]
	s_ashr_i32 s65, s64, 31
	global_load_dwordx4 v[60:63], v[0:1], off nt
	global_load_dwordx4 v[56:59], v[0:1], off offset:1024 nt
	global_load_dwordx4 v[52:55], v[0:1], off offset:2048 nt
	global_load_dwordx4 v[48:51], v[0:1], off offset:3072 nt
	v_lshl_add_u64 v[0:1], v[132:133], 0, s[50:51]
	s_lshl_b64 s[64:65], s[64:65], 12
	global_load_dwordx4 v[44:47], v[0:1], off nt
	global_load_dwordx4 v[40:43], v[0:1], off offset:1024 nt
	global_load_dwordx4 v[36:39], v[0:1], off offset:2048 nt
	global_load_dwordx4 v[32:35], v[0:1], off offset:3072 nt
	v_lshl_add_u64 v[0:1], v[132:133], 0, s[52:53]
	global_load_dwordx4 v[28:31], v[0:1], off nt
	global_load_dwordx4 v[24:27], v[0:1], off offset:1024 nt
	global_load_dwordx4 v[20:23], v[0:1], off offset:2048 nt
	global_load_dwordx4 v[16:19], v[0:1], off offset:3072 nt
	v_lshl_add_u64 v[0:1], v[132:133], 0, s[64:65]
	global_load_dwordx4 v[12:15], v[0:1], off nt
	global_load_dwordx4 v[8:11], v[0:1], off offset:1024 nt
	global_load_dwordx4 v[4:7], v[0:1], off offset:2048 nt
	s_nop 0
	global_load_dwordx4 v[0:3], v[0:1], off offset:3072 nt
	s_waitcnt vmcnt(31)
	v_mul_f32_e32 v128, v125, v125
	v_mul_f32_e32 v146, v127, v127
	s_waitcnt vmcnt(30)
	v_mul_f32_e32 v147, v121, v121
	v_mul_f32_e32 v148, v123, v123
	s_waitcnt vmcnt(29)
	v_mul_f32_e32 v149, v117, v117
	v_mul_f32_e32 v150, v119, v119
	v_fmac_f32_e32 v128, v124, v124
	v_fmac_f32_e32 v146, v126, v126
	v_fmac_f32_e32 v147, v120, v120
	v_fmac_f32_e32 v148, v122, v122
	s_waitcnt vmcnt(28)
	v_mul_f32_e32 v151, v113, v113
	v_mul_f32_e32 v154, v115, v115
	v_fmac_f32_e32 v149, v116, v116
	v_fmac_f32_e32 v150, v118, v118
	v_add_f32_e32 v128, v128, v146
	v_add_f32_e32 v146, v147, v148
	v_fmac_f32_e32 v151, v112, v112
	v_fmac_f32_e32 v154, v114, v114
	v_add_f32_e32 v147, v149, v150
	v_add_f32_e32 v128, v146, v128
	v_add_f32_e32 v148, v151, v154
	v_add_f32_e32 v128, v147, v128
	v_add_f32_e32 v128, v148, v128
	ds_bpermute_b32 v146, v140, v128
	s_waitcnt lgkmcnt(0)
	v_add_f32_e32 v128, v128, v146
	ds_bpermute_b32 v146, v141, v128
	s_waitcnt lgkmcnt(0)
	v_add_f32_e32 v128, v128, v146
	ds_bpermute_b32 v146, v142, v128
	s_waitcnt lgkmcnt(0)
	v_add_f32_e32 v128, v128, v146
	ds_bpermute_b32 v146, v143, v128
	s_waitcnt lgkmcnt(0)
	v_add_f32_e32 v128, v128, v146
	ds_bpermute_b32 v146, v144, v128
	s_waitcnt lgkmcnt(0)
	v_add_f32_e32 v128, v128, v146
	ds_bpermute_b32 v146, v145, v128
	s_and_saveexec_b64 s[38:39], s[2:3]
	s_cbranch_execz .LBB0_442
	s_add_u32 s50, s74, s48
	s_waitcnt lgkmcnt(0)
	v_add_f32_e32 v128, v128, v146
	s_addc_u32 s51, s75, s49
	global_store_dword v129, v128, s[50:51]
